# g3 + RG-LRU conv table re-laid out pair-interleaved in LDS: ds_read_b128 returns ready weight pairs, 48 v_mov per block removed
# baseline (speedup 1.0000x reference)
.LBB0_215:
	s_waitcnt vmcnt(0)
	s_mov_b64 s[0:1], 0x1000
	v_lshl_add_u64 v[16:17], v[118:119], 0, s[0:1]
	v_lshl_add_u64 v[4:5], v[16:17], 0, v[2:3]
	v_mov_b64_e32 v[50:51], v[4:5]
	v_mov_b64_e32 v[8:9], v[150:151]
	v_readlane_b32 s4, v244, 0
	v_readlane_b32 s8, v244, 4
	v_readlane_b32 s9, v244, 5
	v_mov_b32_e32 v14, v130
	s_nop 1
	v_permlane16_swap_b32 v14, v130
	v_readlane_b32 s5, v244, 1
	v_readlane_b32 s6, v244, 2
	v_readlane_b32 s7, v244, 3
	v_readlane_b32 s4, v244, 57
	global_load_dwordx4 v[4:7], v114, s[8:9] offset:3072
	v_mov_b64_e32 v[52:53], v[152:153]
	v_mov_b64_e32 v[54:55], v[154:155]
	v_mov_b64_e32 v[56:57], v[156:157]
	global_load_dwordx4 v[58:61], v114, s[8:9] offset:3136
	global_load_dwordx4 v[62:65], v114, s[8:9] offset:3200
	global_load_dwordx4 v[66:69], v114, s[8:9] offset:3264
	v_mov_b64_e32 v[70:71], v[158:159]
	global_load_dwordx4 v[72:75], v114, s[8:9] offset:3328
	v_mov_b64_e32 v[76:77], v[160:161]
	v_mov_b64_e32 v[78:79], v[162:163]
	v_mov_b64_e32 v[80:81], v[164:165]
	global_load_dwordx4 v[82:85], v114, s[8:9] offset:3392
	global_load_dwordx4 v[86:89], v114, s[8:9] offset:3456
	global_load_dwordx4 v[90:93], v114, s[8:9] offset:3520
	v_mov_b64_e32 v[94:95], v[166:167]
	global_load_dwordx4 v[96:99], v114, s[8:9] offset:3584
	v_mov_b64_e32 v[100:101], v[168:169]
	v_mov_b64_e32 v[102:103], v[248:249]
	v_mov_b64_e32 v[104:105], v[250:251]
	global_load_dwordx4 v[106:109], v114, s[8:9] offset:3648
	global_load_dwordx4 v[120:123], v114, s[8:9] offset:3712
	global_load_dwordx4 v[124:127], v114, s[8:9] offset:3776
	v_mov_b64_e32 v[110:111], v[252:253]
	global_load_dwordx4 v[132:135], v114, s[8:9] offset:3840
	v_mov_b64_e32 v[136:137], v[254:255]
	global_load_dwordx2 v[138:139], v[50:51], off offset:448
	global_load_dwordx2 v[140:141], v[50:51], off offset:480
	global_load_dwordx4 v[142:145], v114, s[8:9] offset:3904
	global_load_dwordx4 v[146:149], v114, s[8:9] offset:3968
	global_load_dwordx4 v[150:153], v114, s[8:9] offset:4032
	v_readlane_b32 s24, v244, 16
	v_readlane_b32 s25, v244, 17
	v_readlane_b32 s26, v244, 42
	v_readlane_b32 s27, v244, 43
	v_readlane_b32 s28, v244, 44
	v_readlane_b32 s29, v244, 45
	v_readlane_b32 s30, v244, 10
	v_readlane_b32 s31, v244, 11
	v_readlane_b32 s32, v244, 14
	v_readlane_b32 s33, v244, 15
	v_readlane_b32 s34, v244, 48
	v_readlane_b32 s35, v244, 49
	v_lshlrev_b32_e32 v113, 2, v0
	v_and_b32_e32 v129, 63, v0
	v_lshrrev_b32_e32 v179, 6, v0
	v_lshlrev_b32_e32 v129, 4, v129
	v_add_u32_e32 v128, 0x1000, v113
	v_lshl_add_u32 v129, v179, 13, v129
	s_add_u32 s36, s34, 0x10000
	s_addc_u32 s37, s35, 0
	v_add_u32_e32 v179, 0x1000, v129
	global_load_dword v154, v113, s[24:25]
	global_load_dword v155, v113, s[26:27]
	global_load_dword v168, v113, s[26:27] offset:2048
	global_load_dword v169, v128, s[26:27]
	global_load_dword v171, v128, s[26:27] offset:2048
	global_load_dword v240, v113, s[28:29]
	global_load_dword v241, v113, s[30:31]
	global_load_dword v242, v113, s[32:33]
	global_load_dwordx4 v[156:159], v129, s[34:35]
	global_load_dwordx4 v[160:163], v129, s[34:35] offset:1024
	global_load_dwordx4 v[164:167], v129, s[34:35] offset:2048
	global_load_dwordx4 v[172:175], v129, s[34:35] offset:3072
	global_load_dwordx4 v[196:199], v129, s[36:37]
	global_load_dwordx4 v[200:203], v129, s[36:37] offset:1024
	global_load_dwordx4 v[204:207], v129, s[36:37] offset:2048
	global_load_dwordx4 v[208:211], v129, s[36:37] offset:3072
	global_load_dwordx4 v[212:215], v179, s[34:35]
	global_load_dwordx4 v[216:219], v179, s[36:37]
	global_load_dwordx4 v[220:223], v179, s[34:35] offset:1024
	global_load_dwordx4 v[224:227], v179, s[36:37] offset:1024
	global_load_dwordx4 v[228:231], v179, s[34:35] offset:2048
	global_load_dwordx4 v[232:235], v179, s[36:37] offset:2048
	global_load_dwordx4 v[236:239], v179, s[34:35] offset:3072
	global_load_dwordx4 v[248:251], v179, s[36:37] offset:3072
	s_waitcnt lgkmcnt(0)
	v_add_f32_e32 v14, v130, v14
	v_mov_b32_e32 v15, v14
	s_nop 1
	v_permlane32_swap_b32 v15, v14
	v_lshlrev_b64 v[10:11], 11, v[116:117]
	v_readlane_b32 s6, v244, 59
	v_readlane_b32 s7, v244, 60
	v_add_u32_e32 v12, s96, v131
	s_mov_b64 s[0:1], 0xdde0600
	v_or_b32_e32 v22, 32, v2
	v_mov_b32_e32 v23, v3
	v_or_b32_e32 v24, 64, v2
	v_mov_b32_e32 v25, v3
	v_or_b32_e32 v18, 0x60, v2
	v_mov_b32_e32 v19, v3
	v_lshl_add_u64 v[10:11], s[6:7], 0, v[10:11]
	s_waitcnt lgkmcnt(0)
	v_add_f32_e32 v14, v14, v15
	v_add3_u32 v26, v12, v115, v2
	v_lshl_add_u64 v[12:13], v[10:11], 0, s[0:1]
	v_lshl_add_u64 v[10:11], v[16:17], 0, v[22:23]
	v_lshl_add_u64 v[20:21], v[16:17], 0, v[24:25]
	v_lshl_add_u64 v[32:33], v[16:17], 0, v[18:19]
	v_fmamk_f32 v14, v14, 0x3b800000, v180
	s_mov_b32 s0, 0x800000
	ds_read2_b64 v[28:31], v26 offset1:4
	s_nop 0
	s_nop 0
	v_mul_f32_e32 v15, 0x4b800000, v14
	v_cmp_gt_f32_e32 vcc, s0, v14
	v_lshl_add_u64 v[34:35], v[12:13], 0, v[2:3]
	s_waitcnt lgkmcnt(0)
	v_lshlrev_b32_e32 v33, 16, v28
	v_cndmask_b32_e32 v14, v14, v15, vcc
	v_rsq_f32_e32 v14, v14
	v_and_b32_e32 v39, 0xffff0000, v28
	v_lshlrev_b32_e32 v41, 16, v29
	v_and_b32_e32 v29, 0xffff0000, v29
	v_mul_f32_e32 v15, 0x45800000, v14
	v_cndmask_b32_e32 v15, v14, v15, vcc
	v_lshl_add_u64 v[18:19], v[12:13], 0, v[18:19]
	v_mov_b32_e32 v44, v15
	v_mov_b32_e32 v46, v15
	v_mov_b32_e32 v48, v15
	v_readlane_b32 s36, v244, 10
	v_readlane_b32 s42, v244, 16
	v_readlane_b32 s43, v244, 17
	v_readlane_b32 s10, v244, 6
	v_readlane_b32 s11, v244, 7
	v_readlane_b32 s5, v244, 58
	s_movk_i32 s0, 0x1000
	v_readlane_b32 s37, v244, 11
	v_readlane_b32 s40, v244, 14
	v_readlane_b32 s41, v244, 15
	s_mov_b32 s3, 0x7f800000
	s_mov_b32 s2, 0x33800000
	v_readlane_b32 s38, v244, 12
	v_readlane_b32 s39, v244, 13
	v_readlane_b32 s44, v244, 18
	v_readlane_b32 s45, v244, 19
	v_readlane_b32 s46, v244, 20
	v_readlane_b32 s47, v244, 21
	v_readlane_b32 s48, v244, 22
	v_readlane_b32 s49, v244, 23
	v_readlane_b32 s50, v244, 24
	v_readlane_b32 s51, v244, 25
	v_lshlrev_b32_e32 v32, 16, v8
	v_and_b32_e32 v38, 0xffff0000, v8
	v_mul_f32_e32 v8, 0xbfb8aa3b, v32
	v_exp_f32_e32 v8, v8
	v_lshlrev_b32_e32 v40, 16, v9
	v_and_b32_e32 v28, 0xffff0000, v9
	v_mul_f32_e32 v9, 0xbfb8aa3b, v38
	v_exp_f32_e32 v9, v9
	v_add_f32_e32 v8, 1.0, v8
	v_rcp_f32_e32 v14, v8
	v_mul_f32_e32 v27, 0xbfb8aa3b, v40
	v_exp_f32_e32 v27, v27
	v_add_f32_e32 v43, 1.0, v9
	v_pk_mul_f32 v[8:9], v[14:15], v[32:33]
	v_rcp_f32_e32 v14, v43
	v_mul_f32_e32 v42, 0xbfb8aa3b, v28
	v_exp_f32_e32 v42, v42
	v_add_f32_e32 v27, 1.0, v27
	v_pk_mul_f32 v[32:33], v[14:15], v[38:39]
	v_rcp_f32_e32 v14, v27
	s_waitcnt vmcnt(41)
	v_mul_f32_e32 v4, v4, v9
	v_add_f32_e32 v42, 1.0, v42
	v_mul_f32_e32 v8, v8, v4
	v_mul_f32_e32 v4, v5, v33
	v_mul_f32_e32 v9, v32, v4
	v_pk_mul_f32 v[4:5], v[14:15], v[40:41]
	v_rcp_f32_e32 v14, v42
	v_mul_f32_e32 v5, v6, v5
	v_mul_f32_e32 v6, v4, v5
	v_cvt_pk_bf16_f32 v8, v8, v9
	v_pk_mul_f32 v[4:5], v[14:15], v[28:29]
	v_and_b32_e32 v29, 0xffff0000, v52
	v_mul_f32_e32 v5, v7, v5
	v_mul_f32_e32 v4, v4, v5
	v_cvt_pk_bf16_f32 v9, v6, v4
	global_store_dwordx2 v[34:35], v[8:9], off
	v_lshl_add_u64 v[8:9], v[12:13], 0, v[22:23]
	v_lshlrev_b32_e32 v23, 16, v52
	v_lshlrev_b32_e32 v22, 16, v30
	v_and_b32_e32 v28, 0xffff0000, v30
	v_lshlrev_b32_e32 v30, 16, v31
	v_and_b32_e32 v32, 0xffff0000, v31
	v_lshlrev_b32_e32 v31, 16, v53
	v_and_b32_e32 v33, 0xffff0000, v53
	v_mul_f32_e32 v10, 0xbfb8aa3b, v23
	v_mul_f32_e32 v11, 0xbfb8aa3b, v29
	v_mul_f32_e32 v14, 0xbfb8aa3b, v31
	v_mul_f32_e32 v27, 0xbfb8aa3b, v33
	v_exp_f32_e32 v10, v10
	v_exp_f32_e32 v11, v11
	v_exp_f32_e32 v14, v14
	v_exp_f32_e32 v27, v27
	v_add_f32_e32 v10, 1.0, v10
	v_add_f32_e32 v11, 1.0, v11
	v_add_f32_e32 v14, 1.0, v14
	v_add_f32_e32 v27, 1.0, v27
	v_rcp_f32_e32 v35, v10
	v_rcp_f32_e32 v39, v11
	v_rcp_f32_e32 v41, v14
	v_rcp_f32_e32 v43, v27
	v_mov_b32_e32 v34, v15
	v_mov_b32_e32 v38, v15
	v_mov_b32_e32 v40, v15
	v_mov_b32_e32 v42, v15
	v_pk_mul_f32 v[10:11], v[34:35], v[22:23]
	v_pk_mul_f32 v[22:23], v[38:39], v[28:29]
	v_pk_mul_f32 v[28:29], v[40:41], v[30:31]
	v_pk_mul_f32 v[30:31], v[42:43], v[32:33]
	v_mov_b32_e32 v32, v15
	s_waitcnt vmcnt(41)
	v_mul_f32_e32 v4, v58, v10
	v_mul_f32_e32 v5, v59, v22
	v_mul_f32_e32 v6, v60, v28
	v_mul_f32_e32 v7, v61, v30
	v_mul_f32_e32 v4, v4, v11
	v_mul_f32_e32 v5, v5, v23
	v_mul_f32_e32 v6, v6, v29
	v_mul_f32_e32 v7, v7, v31
	v_cvt_pk_bf16_f32 v4, v4, v5
	v_cvt_pk_bf16_f32 v5, v6, v7
	global_store_dwordx2 v[8:9], v[4:5], off
	ds_read2_b64 v[4:7], v26 offset0:8 offset1:12
	v_lshlrev_b32_e32 v29, 16, v55
	v_lshl_add_u64 v[22:23], v[12:13], 0, v[24:25]
	v_lshlrev_b32_e32 v25, 16, v54
	v_and_b32_e32 v31, 0xffff0000, v55
	s_waitcnt lgkmcnt(0)
	v_lshlrev_b32_e32 v28, 16, v5
	v_and_b32_e32 v30, 0xffff0000, v5
	v_and_b32_e32 v5, 0xffff0000, v54
	v_mul_f32_e32 v27, 0xbfb8aa3b, v5
	v_mul_f32_e32 v33, 0xbfb8aa3b, v29
	v_mul_f32_e32 v14, 0xbfb8aa3b, v25
	v_mul_f32_e32 v35, 0xbfb8aa3b, v31
	v_exp_f32_e32 v27, v27
	v_exp_f32_e32 v33, v33
	v_exp_f32_e32 v14, v14
	v_exp_f32_e32 v35, v35
	v_add_f32_e32 v27, 1.0, v27
	v_add_f32_e32 v36, 1.0, v33
	v_add_f32_e32 v14, 1.0, v14
	v_add_f32_e32 v37, 1.0, v35
	v_rcp_f32_e32 v35, v27
	v_rcp_f32_e32 v39, v36
	v_rcp_f32_e32 v33, v14
	v_rcp_f32_e32 v41, v37
	v_lshlrev_b32_e32 v24, 16, v4
	v_and_b32_e32 v4, 0xffff0000, v4
	v_pk_mul_f32 v[4:5], v[34:35], v[4:5]
	v_pk_mul_f32 v[28:29], v[38:39], v[28:29]
	v_pk_mul_f32 v[24:25], v[32:33], v[24:25]
	v_pk_mul_f32 v[30:31], v[40:41], v[30:31]
	v_mov_b32_e32 v36, v15
	s_waitcnt vmcnt(41)
	v_mul_f32_e32 v4, v63, v4
	v_mul_f32_e32 v9, v64, v28
	v_mul_f32_e32 v8, v62, v24
	v_mul_f32_e32 v10, v65, v30
	v_mul_f32_e32 v4, v4, v5
	v_mul_f32_e32 v5, v9, v29
	v_mul_f32_e32 v8, v8, v25
	v_mul_f32_e32 v9, v10, v31
	v_cvt_pk_bf16_f32 v4, v8, v4
	v_cvt_pk_bf16_f32 v5, v5, v9
	global_store_dwordx2 v[22:23], v[4:5], off
	v_or_b32_e32 v10, 0x80, v2
	v_mov_b32_e32 v11, v3
	v_lshl_add_u64 v[4:5], v[16:17], 0, v[10:11]
	v_lshlrev_b32_e32 v28, 16, v7
	v_and_b32_e32 v30, 0xffff0000, v7
	v_lshlrev_b32_e32 v5, 16, v56
	v_and_b32_e32 v7, 0xffff0000, v56
	v_lshlrev_b32_e32 v29, 16, v57
	v_and_b32_e32 v31, 0xffff0000, v57
	v_mul_f32_e32 v14, 0xbfb8aa3b, v5
	v_mul_f32_e32 v20, 0xbfb8aa3b, v7
	v_mul_f32_e32 v21, 0xbfb8aa3b, v29
	v_mul_f32_e32 v27, 0xbfb8aa3b, v31
	v_exp_f32_e32 v14, v14
	v_exp_f32_e32 v20, v20
	v_exp_f32_e32 v21, v21
	v_exp_f32_e32 v27, v27
	v_add_f32_e32 v14, 1.0, v14
	v_add_f32_e32 v20, 1.0, v20
	v_add_f32_e32 v21, 1.0, v21
	v_add_f32_e32 v27, 1.0, v27
	v_rcp_f32_e32 v33, v14
	v_rcp_f32_e32 v35, v20
	v_rcp_f32_e32 v37, v21
	v_rcp_f32_e32 v39, v27
	v_lshlrev_b32_e32 v4, 16, v6
	v_and_b32_e32 v6, 0xffff0000, v6
	v_pk_mul_f32 v[4:5], v[32:33], v[4:5]
	v_pk_mul_f32 v[6:7], v[34:35], v[6:7]
	v_pk_mul_f32 v[20:21], v[36:37], v[28:29]
	v_pk_mul_f32 v[28:29], v[38:39], v[30:31]
	v_lshl_add_u64 v[10:11], v[12:13], 0, v[10:11]
	s_waitcnt vmcnt(41)
	v_mul_f32_e32 v4, v66, v4
	v_mul_f32_e32 v6, v67, v6
	v_mul_f32_e32 v14, v68, v20
	v_mul_f32_e32 v20, v69, v28
	v_mul_f32_e32 v4, v4, v5
	v_mul_f32_e32 v5, v6, v7
	v_mul_f32_e32 v6, v14, v21
	v_mul_f32_e32 v7, v20, v29
	v_cvt_pk_bf16_f32 v4, v4, v5
	v_cvt_pk_bf16_f32 v5, v6, v7
	global_store_dwordx2 v[18:19], v[4:5], off
	ds_read2_b64 v[28:31], v26 offset0:16 offset1:20
	v_or_b32_e32 v22, 0xa0, v2
	v_mov_b32_e32 v23, v3
	v_or_b32_e32 v24, 0xc0, v2
	v_mov_b32_e32 v25, v3
	v_or_b32_e32 v18, 0xe0, v2
	v_mov_b32_e32 v19, v3
	v_lshl_add_u64 v[20:21], v[16:17], 0, v[22:23]
	v_lshl_add_u64 v[32:33], v[16:17], 0, v[24:25]
	v_lshl_add_u64 v[34:35], v[16:17], 0, v[18:19]
	s_nop 0
	s_nop 0
	s_waitcnt lgkmcnt(0)
	v_lshlrev_b32_e32 v38, 16, v29
	v_and_b32_e32 v40, 0xffff0000, v29
	v_lshlrev_b32_e32 v35, 16, v70
	v_and_b32_e32 v29, 0xffff0000, v70
	v_lshlrev_b32_e32 v39, 16, v71
	v_and_b32_e32 v41, 0xffff0000, v71
	v_mul_f32_e32 v8, 0xbfb8aa3b, v35
	v_mul_f32_e32 v9, 0xbfb8aa3b, v29
	v_mul_f32_e32 v14, 0xbfb8aa3b, v39
	v_mul_f32_e32 v27, 0xbfb8aa3b, v41
	v_exp_f32_e32 v8, v8
	v_exp_f32_e32 v9, v9
	v_exp_f32_e32 v14, v14
	v_exp_f32_e32 v27, v27
	v_add_f32_e32 v8, 1.0, v8
	v_add_f32_e32 v9, 1.0, v9
	v_add_f32_e32 v14, 1.0, v14
	v_add_f32_e32 v27, 1.0, v27
	v_rcp_f32_e32 v43, v8
	v_rcp_f32_e32 v45, v9
	v_rcp_f32_e32 v47, v14
	v_rcp_f32_e32 v49, v27
	v_lshlrev_b32_e32 v34, 16, v28
	v_and_b32_e32 v28, 0xffff0000, v28
	v_pk_mul_f32 v[8:9], v[42:43], v[34:35]
	v_pk_mul_f32 v[28:29], v[44:45], v[28:29]
	v_pk_mul_f32 v[34:35], v[46:47], v[38:39]
	v_pk_mul_f32 v[38:39], v[48:49], v[40:41]
	v_mov_b32_e32 v40, v15
	v_lshl_add_u64 v[18:19], v[12:13], 0, v[18:19]
	s_waitcnt vmcnt(41)
	v_mul_f32_e32 v4, v72, v8
	v_mul_f32_e32 v5, v73, v28
	v_mul_f32_e32 v6, v74, v34
	v_mul_f32_e32 v7, v75, v38
	v_mul_f32_e32 v4, v4, v9
	v_mul_f32_e32 v5, v5, v29
	v_mul_f32_e32 v6, v6, v35
	v_mul_f32_e32 v7, v7, v39
	v_cvt_pk_bf16_f32 v4, v4, v5
	v_cvt_pk_bf16_f32 v5, v6, v7
	global_store_dwordx2 v[10:11], v[4:5], off
	v_lshl_add_u64 v[8:9], v[12:13], 0, v[22:23]
	v_lshlrev_b32_e32 v11, 16, v76
	v_and_b32_e32 v23, 0xffff0000, v76
	v_lshlrev_b32_e32 v10, 16, v30
	v_and_b32_e32 v22, 0xffff0000, v30
	v_lshlrev_b32_e32 v28, 16, v31
	v_and_b32_e32 v30, 0xffff0000, v31
	v_lshlrev_b32_e32 v29, 16, v77
	v_and_b32_e32 v31, 0xffff0000, v77
	v_mul_f32_e32 v14, 0xbfb8aa3b, v11
	v_mul_f32_e32 v27, 0xbfb8aa3b, v23
	v_mul_f32_e32 v35, 0xbfb8aa3b, v29
	v_mul_f32_e32 v36, 0xbfb8aa3b, v31
	v_exp_f32_e32 v14, v14
	v_exp_f32_e32 v27, v27
	v_exp_f32_e32 v35, v35
	v_exp_f32_e32 v36, v36
	v_add_f32_e32 v14, 1.0, v14
	v_add_f32_e32 v27, 1.0, v27
	v_add_f32_e32 v37, 1.0, v35
	v_add_f32_e32 v36, 1.0, v36
	v_rcp_f32_e32 v35, v14
	v_rcp_f32_e32 v39, v27
	v_rcp_f32_e32 v41, v37
	v_rcp_f32_e32 v43, v36
	v_mov_b32_e32 v34, v15
	v_mov_b32_e32 v38, v15
	v_pk_mul_f32 v[10:11], v[34:35], v[10:11]
	v_pk_mul_f32 v[22:23], v[38:39], v[22:23]
	v_pk_mul_f32 v[28:29], v[40:41], v[28:29]
	v_pk_mul_f32 v[30:31], v[42:43], v[30:31]
	v_mov_b32_e32 v36, v15
	s_waitcnt vmcnt(41)
	v_mul_f32_e32 v4, v82, v10
	v_mul_f32_e32 v5, v83, v22
	v_mul_f32_e32 v6, v84, v28
	v_mul_f32_e32 v7, v85, v30
	v_mul_f32_e32 v4, v4, v11
	v_mul_f32_e32 v5, v5, v23
	v_mul_f32_e32 v6, v6, v29
	v_mul_f32_e32 v7, v7, v31
	v_cvt_pk_bf16_f32 v4, v4, v5
	v_cvt_pk_bf16_f32 v5, v6, v7
	global_store_dwordx2 v[8:9], v[4:5], off
	ds_read2_b64 v[4:7], v26 offset0:24 offset1:28
	v_lshlrev_b32_e32 v29, 16, v79
	v_lshl_add_u64 v[22:23], v[12:13], 0, v[24:25]
	v_lshlrev_b32_e32 v25, 16, v78
	v_and_b32_e32 v31, 0xffff0000, v79
	s_waitcnt lgkmcnt(0)
	v_lshlrev_b32_e32 v28, 16, v5
	v_and_b32_e32 v30, 0xffff0000, v5
	v_and_b32_e32 v5, 0xffff0000, v78
	v_mul_f32_e32 v27, 0xbfb8aa3b, v5
	v_mul_f32_e32 v32, 0xbfb8aa3b, v29
	v_mul_f32_e32 v14, 0xbfb8aa3b, v25
	v_mul_f32_e32 v33, 0xbfb8aa3b, v31
	v_exp_f32_e32 v27, v27
	v_exp_f32_e32 v32, v32
	v_exp_f32_e32 v14, v14
	v_exp_f32_e32 v33, v33
	v_add_f32_e32 v27, 1.0, v27
	v_add_f32_e32 v32, 1.0, v32
	v_add_f32_e32 v14, 1.0, v14
	v_add_f32_e32 v33, 1.0, v33
	v_rcp_f32_e32 v37, v27
	v_rcp_f32_e32 v39, v32
	v_rcp_f32_e32 v35, v14
	v_rcp_f32_e32 v41, v33
	v_lshlrev_b32_e32 v24, 16, v4
	v_and_b32_e32 v4, 0xffff0000, v4
	v_pk_mul_f32 v[4:5], v[36:37], v[4:5]
	v_pk_mul_f32 v[28:29], v[38:39], v[28:29]
	v_pk_mul_f32 v[24:25], v[34:35], v[24:25]
	v_pk_mul_f32 v[30:31], v[40:41], v[30:31]
	v_mov_b32_e32 v32, v15
	s_waitcnt vmcnt(41)
	v_mul_f32_e32 v4, v87, v4
	v_mul_f32_e32 v9, v88, v28
	v_mul_f32_e32 v8, v86, v24
	v_mul_f32_e32 v10, v89, v30
	v_mul_f32_e32 v4, v4, v5
	v_mul_f32_e32 v5, v9, v29
	v_mul_f32_e32 v8, v8, v25
	v_mul_f32_e32 v9, v10, v31
	v_cvt_pk_bf16_f32 v4, v8, v4
	v_cvt_pk_bf16_f32 v5, v5, v9
	global_store_dwordx2 v[22:23], v[4:5], off
	v_or_b32_e32 v10, 0x100, v2
	v_mov_b32_e32 v11, v3
	v_lshl_add_u64 v[4:5], v[16:17], 0, v[10:11]
	v_lshlrev_b32_e32 v28, 16, v7
	v_and_b32_e32 v30, 0xffff0000, v7
	v_lshlrev_b32_e32 v5, 16, v80
	v_and_b32_e32 v7, 0xffff0000, v80
	v_lshlrev_b32_e32 v29, 16, v81
	v_and_b32_e32 v31, 0xffff0000, v81
	v_mul_f32_e32 v14, 0xbfb8aa3b, v5
	v_mul_f32_e32 v20, 0xbfb8aa3b, v7
	v_mul_f32_e32 v21, 0xbfb8aa3b, v29
	v_mul_f32_e32 v27, 0xbfb8aa3b, v31
	v_exp_f32_e32 v14, v14
	v_exp_f32_e32 v20, v20
	v_exp_f32_e32 v21, v21
	v_exp_f32_e32 v27, v27
	v_add_f32_e32 v14, 1.0, v14
	v_add_f32_e32 v20, 1.0, v20
	v_add_f32_e32 v21, 1.0, v21
	v_add_f32_e32 v27, 1.0, v27
	v_rcp_f32_e32 v33, v14
	v_rcp_f32_e32 v35, v20
	v_rcp_f32_e32 v37, v21
	v_rcp_f32_e32 v39, v27
	v_lshlrev_b32_e32 v4, 16, v6
	v_and_b32_e32 v6, 0xffff0000, v6
	v_pk_mul_f32 v[4:5], v[32:33], v[4:5]
	v_pk_mul_f32 v[6:7], v[34:35], v[6:7]
	v_pk_mul_f32 v[20:21], v[36:37], v[28:29]
	v_pk_mul_f32 v[28:29], v[38:39], v[30:31]
	v_lshl_add_u64 v[36:37], v[12:13], 0, v[10:11]
	s_waitcnt vmcnt(41)
	v_mul_f32_e32 v4, v90, v4
	v_mul_f32_e32 v6, v91, v6
	v_mul_f32_e32 v14, v92, v20
	v_mul_f32_e32 v20, v93, v28
	v_mul_f32_e32 v4, v4, v5
	v_mul_f32_e32 v5, v6, v7
	v_mul_f32_e32 v6, v14, v21
	v_mul_f32_e32 v7, v20, v29
	v_cvt_pk_bf16_f32 v4, v4, v5
	v_cvt_pk_bf16_f32 v5, v6, v7
	global_store_dwordx2 v[18:19], v[4:5], off
	ds_read2_b64 v[28:31], v26 offset0:32 offset1:36
	v_or_b32_e32 v20, 0x120, v2
	v_mov_b32_e32 v21, v3
	v_or_b32_e32 v22, 0x140, v2
	v_mov_b32_e32 v23, v3
	v_or_b32_e32 v18, 0x160, v2
	v_mov_b32_e32 v19, v3
	v_lshl_add_u64 v[24:25], v[16:17], 0, v[20:21]
	v_lshl_add_u64 v[32:33], v[16:17], 0, v[22:23]
	v_lshl_add_u64 v[34:35], v[16:17], 0, v[18:19]
	s_nop 0
	s_nop 0
	s_waitcnt lgkmcnt(0)
	v_lshlrev_b32_e32 v38, 16, v29
	v_and_b32_e32 v40, 0xffff0000, v29
	v_lshlrev_b32_e32 v35, 16, v94
	v_and_b32_e32 v29, 0xffff0000, v94
	v_lshlrev_b32_e32 v39, 16, v95
	v_and_b32_e32 v41, 0xffff0000, v95
	v_mul_f32_e32 v8, 0xbfb8aa3b, v35
	v_mul_f32_e32 v9, 0xbfb8aa3b, v29
	v_mul_f32_e32 v14, 0xbfb8aa3b, v39
	v_mul_f32_e32 v27, 0xbfb8aa3b, v41
	v_exp_f32_e32 v8, v8
	v_exp_f32_e32 v9, v9
	v_exp_f32_e32 v14, v14
	v_exp_f32_e32 v27, v27
	v_add_f32_e32 v8, 1.0, v8
	v_add_f32_e32 v9, 1.0, v9
	v_add_f32_e32 v14, 1.0, v14
	v_add_f32_e32 v27, 1.0, v27
	v_rcp_f32_e32 v43, v8
	v_rcp_f32_e32 v45, v9
	v_rcp_f32_e32 v47, v14
	v_rcp_f32_e32 v49, v27
	v_lshlrev_b32_e32 v34, 16, v28
	v_and_b32_e32 v28, 0xffff0000, v28
	v_pk_mul_f32 v[8:9], v[42:43], v[34:35]
	v_pk_mul_f32 v[28:29], v[44:45], v[28:29]
	v_pk_mul_f32 v[34:35], v[46:47], v[38:39]
	v_pk_mul_f32 v[38:39], v[48:49], v[40:41]
	v_mov_b32_e32 v40, v15
	s_waitcnt vmcnt(41)
	v_mul_f32_e32 v4, v96, v8
	v_mul_f32_e32 v5, v97, v28
	v_mul_f32_e32 v6, v98, v34
	v_mul_f32_e32 v7, v99, v38
	v_mul_f32_e32 v4, v4, v9
	v_mul_f32_e32 v5, v5, v29
	v_mul_f32_e32 v6, v6, v35
	v_mul_f32_e32 v7, v7, v39
	v_cvt_pk_bf16_f32 v4, v4, v5
	v_cvt_pk_bf16_f32 v5, v6, v7
	global_store_dwordx2 v[36:37], v[4:5], off
	v_lshl_add_u64 v[8:9], v[12:13], 0, v[20:21]
	v_lshlrev_b32_e32 v21, 16, v100
	v_and_b32_e32 v29, 0xffff0000, v100
	v_lshlrev_b32_e32 v20, 16, v30
	v_and_b32_e32 v28, 0xffff0000, v30
	v_lshlrev_b32_e32 v30, 16, v31
	v_and_b32_e32 v34, 0xffff0000, v31
	v_lshlrev_b32_e32 v31, 16, v101
	v_and_b32_e32 v35, 0xffff0000, v101
	v_mul_f32_e32 v14, 0xbfb8aa3b, v21
	v_mul_f32_e32 v24, 0xbfb8aa3b, v29
	v_mul_f32_e32 v25, 0xbfb8aa3b, v31
	v_mul_f32_e32 v27, 0xbfb8aa3b, v35
	v_exp_f32_e32 v14, v14
	v_exp_f32_e32 v24, v24
	v_exp_f32_e32 v25, v25
	v_exp_f32_e32 v27, v27
	v_add_f32_e32 v14, 1.0, v14
	v_add_f32_e32 v24, 1.0, v24
	v_add_f32_e32 v25, 1.0, v25
	v_add_f32_e32 v27, 1.0, v27
	v_rcp_f32_e32 v37, v14
	v_rcp_f32_e32 v39, v24
	v_rcp_f32_e32 v41, v25
	v_rcp_f32_e32 v43, v27
	v_mov_b32_e32 v36, v15
	v_mov_b32_e32 v38, v15
	v_pk_mul_f32 v[20:21], v[36:37], v[20:21]
	v_pk_mul_f32 v[24:25], v[38:39], v[28:29]
	v_pk_mul_f32 v[28:29], v[40:41], v[30:31]
	v_pk_mul_f32 v[30:31], v[42:43], v[34:35]
	v_mov_b32_e32 v34, v15
	s_waitcnt vmcnt(41)
	v_mul_f32_e32 v4, v106, v20
	v_mul_f32_e32 v5, v107, v24
	v_mul_f32_e32 v6, v108, v28
	v_mul_f32_e32 v7, v109, v30
	v_mul_f32_e32 v4, v4, v21
	v_mul_f32_e32 v5, v5, v25
	v_mul_f32_e32 v6, v6, v29
	v_mul_f32_e32 v7, v7, v31
	v_cvt_pk_bf16_f32 v4, v4, v5
	v_cvt_pk_bf16_f32 v5, v6, v7
	global_store_dwordx2 v[8:9], v[4:5], off
	ds_read2_b64 v[4:7], v26 offset0:40 offset1:44
	v_lshl_add_u64 v[8:9], v[12:13], 0, v[22:23]
	v_lshlrev_b32_e32 v21, 16, v102
	v_lshlrev_b32_e32 v23, 16, v103
	v_and_b32_e32 v25, 0xffff0000, v103
	s_waitcnt lgkmcnt(0)
	v_lshlrev_b32_e32 v22, 16, v5
	v_and_b32_e32 v24, 0xffff0000, v5
	v_and_b32_e32 v5, 0xffff0000, v102
	v_mul_f32_e32 v14, 0xbfb8aa3b, v21
	v_mul_f32_e32 v27, 0xbfb8aa3b, v5
	v_mul_f32_e32 v32, 0xbfb8aa3b, v23
	v_mul_f32_e32 v33, 0xbfb8aa3b, v25
	v_exp_f32_e32 v14, v14
	v_exp_f32_e32 v27, v27
	v_exp_f32_e32 v32, v32
	v_exp_f32_e32 v33, v33
	v_add_f32_e32 v14, 1.0, v14
	v_add_f32_e32 v27, 1.0, v27
	v_add_f32_e32 v32, 1.0, v32
	v_add_f32_e32 v33, 1.0, v33
	v_rcp_f32_e32 v35, v14
	v_rcp_f32_e32 v37, v27
	v_rcp_f32_e32 v39, v32
	v_rcp_f32_e32 v41, v33
	v_lshlrev_b32_e32 v20, 16, v4
	v_and_b32_e32 v4, 0xffff0000, v4
	v_pk_mul_f32 v[20:21], v[34:35], v[20:21]
	v_pk_mul_f32 v[4:5], v[36:37], v[4:5]
	v_pk_mul_f32 v[22:23], v[38:39], v[22:23]
	v_pk_mul_f32 v[24:25], v[40:41], v[24:25]
	v_mov_b32_e32 v32, v15
	s_waitcnt vmcnt(41)
	v_mul_f32_e32 v14, v120, v20
	v_mul_f32_e32 v4, v121, v4
	v_mul_f32_e32 v20, v122, v22
	v_mul_f32_e32 v22, v123, v24
	v_mul_f32_e32 v4, v4, v5
	v_mul_f32_e32 v5, v20, v23
	v_mul_f32_e32 v14, v14, v21
	v_mul_f32_e32 v20, v22, v25
	v_cvt_pk_bf16_f32 v4, v14, v4
	v_cvt_pk_bf16_f32 v5, v5, v20
	global_store_dwordx2 v[8:9], v[4:5], off
	v_or_b32_e32 v20, 0x180, v2
	v_mov_b32_e32 v21, v3
	v_lshl_add_u64 v[4:5], v[16:17], 0, v[20:21]
	v_lshl_add_u64 v[8:9], v[12:13], 0, v[18:19]
	v_lshlrev_b32_e32 v28, 16, v7
	v_and_b32_e32 v30, 0xffff0000, v7
	v_lshlrev_b32_e32 v5, 16, v104
	v_and_b32_e32 v7, 0xffff0000, v104
	v_lshlrev_b32_e32 v29, 16, v105
	v_and_b32_e32 v31, 0xffff0000, v105
	v_mul_f32_e32 v10, 0xbfb8aa3b, v5
	v_mul_f32_e32 v11, 0xbfb8aa3b, v7
	v_mul_f32_e32 v14, 0xbfb8aa3b, v29
	v_mul_f32_e32 v27, 0xbfb8aa3b, v31
	v_exp_f32_e32 v10, v10
	v_exp_f32_e32 v11, v11
	v_exp_f32_e32 v14, v14
	v_exp_f32_e32 v27, v27
	v_add_f32_e32 v10, 1.0, v10
	v_add_f32_e32 v11, 1.0, v11
	v_add_f32_e32 v14, 1.0, v14
	v_add_f32_e32 v27, 1.0, v27
	v_rcp_f32_e32 v33, v10
	v_rcp_f32_e32 v35, v11
	v_rcp_f32_e32 v37, v14
	v_rcp_f32_e32 v39, v27
	v_lshlrev_b32_e32 v4, 16, v6
	v_and_b32_e32 v6, 0xffff0000, v6
	v_pk_mul_f32 v[4:5], v[32:33], v[4:5]
	v_pk_mul_f32 v[6:7], v[34:35], v[6:7]
	v_pk_mul_f32 v[10:11], v[36:37], v[28:29]
	v_pk_mul_f32 v[28:29], v[38:39], v[30:31]
	v_lshl_add_u64 v[20:21], v[12:13], 0, v[20:21]
	s_waitcnt vmcnt(41)
	v_mul_f32_e32 v4, v124, v4
	v_mul_f32_e32 v6, v125, v6
	v_mul_f32_e32 v10, v126, v10
	v_mul_f32_e32 v14, v127, v28
	v_mul_f32_e32 v4, v4, v5
	v_mul_f32_e32 v5, v6, v7
	v_mul_f32_e32 v6, v10, v11
	v_mul_f32_e32 v7, v14, v29
	v_cvt_pk_bf16_f32 v4, v4, v5
	v_cvt_pk_bf16_f32 v5, v6, v7
	global_store_dwordx2 v[8:9], v[4:5], off
	ds_read2_b64 v[8:11], v26 offset0:48 offset1:52
	v_lshlrev_b32_e32 v33, 16, v110
	v_lshlrev_b32_e32 v35, 16, v111
	v_and_b32_e32 v37, 0xffff0000, v111
	v_mul_f32_e32 v14, 0xbfb8aa3b, v33
	s_waitcnt lgkmcnt(0)
	v_lshlrev_b32_e32 v34, 16, v9
	v_and_b32_e32 v36, 0xffff0000, v9
	v_and_b32_e32 v9, 0xffff0000, v110
	v_mul_f32_e32 v18, 0xbfb8aa3b, v9
	v_mul_f32_e32 v19, 0xbfb8aa3b, v35
	v_mul_f32_e32 v27, 0xbfb8aa3b, v37
	v_exp_f32_e32 v14, v14
	v_exp_f32_e32 v18, v18
	v_or_b32_e32 v22, 0x1a0, v2
	v_mov_b32_e32 v23, v3
	v_or_b32_e32 v24, 0x1c0, v2
	v_mov_b32_e32 v25, v3
	v_or_b32_e32 v2, 0x1e0, v2
	v_exp_f32_e32 v19, v19
	v_exp_f32_e32 v27, v27
	v_lshl_add_u64 v[28:29], v[16:17], 0, v[22:23]
	v_lshl_add_u64 v[30:31], v[16:17], 0, v[24:25]
	v_lshl_add_u64 v[16:17], v[16:17], 0, v[2:3]
	s_nop 0
	s_nop 0
	v_add_f32_e32 v14, 1.0, v14
	v_add_f32_e32 v18, 1.0, v18
	v_add_f32_e32 v19, 1.0, v19
	v_add_f32_e32 v27, 1.0, v27
	v_rcp_f32_e32 v39, v14
	v_rcp_f32_e32 v41, v18
	v_rcp_f32_e32 v43, v19
	v_rcp_f32_e32 v45, v27
	v_lshlrev_b32_e32 v32, 16, v8
	v_and_b32_e32 v8, 0xffff0000, v8
	v_pk_mul_f32 v[18:19], v[38:39], v[32:33]
	v_pk_mul_f32 v[8:9], v[40:41], v[8:9]
	v_pk_mul_f32 v[32:33], v[42:43], v[34:35]
	v_pk_mul_f32 v[34:35], v[44:45], v[36:37]
	v_mov_b32_e32 v36, v15
	v_mov_b32_e32 v42, v0
	s_waitcnt vmcnt(41)
	v_mul_f32_e32 v4, v132, v18
	v_mul_f32_e32 v5, v133, v8
	v_mul_f32_e32 v6, v134, v32
	v_mul_f32_e32 v7, v135, v34
	v_mul_f32_e32 v4, v4, v19
	v_mul_f32_e32 v5, v5, v9
	v_mul_f32_e32 v6, v6, v33
	v_mul_f32_e32 v7, v7, v35
	v_cvt_pk_bf16_f32 v4, v4, v5
	v_cvt_pk_bf16_f32 v5, v6, v7
	global_store_dwordx2 v[20:21], v[4:5], off
	v_lshl_add_u64 v[8:9], v[12:13], 0, v[22:23]
	v_lshlrev_b32_e32 v20, 16, v11
	v_and_b32_e32 v22, 0xffff0000, v11
	v_lshlrev_b32_e32 v18, 16, v10
	v_and_b32_e32 v10, 0xffff0000, v10
	v_mov_b32_e32 v32, v15
	v_mov_b32_e32 v34, v15
	v_lshlrev_b32_e32 v19, 16, v136
	v_and_b32_e32 v11, 0xffff0000, v136
	v_lshlrev_b32_e32 v21, 16, v137
	v_and_b32_e32 v23, 0xffff0000, v137
	v_mul_f32_e32 v14, 0xbfb8aa3b, v19
	v_mul_f32_e32 v27, 0xbfb8aa3b, v11
	v_mul_f32_e32 v28, 0xbfb8aa3b, v21
	v_mul_f32_e32 v29, 0xbfb8aa3b, v23
	v_exp_f32_e32 v14, v14
	v_exp_f32_e32 v27, v27
	v_exp_f32_e32 v28, v28
	v_exp_f32_e32 v29, v29
	v_add_f32_e32 v14, 1.0, v14
	v_add_f32_e32 v27, 1.0, v27
	v_add_f32_e32 v28, 1.0, v28
	v_add_f32_e32 v29, 1.0, v29
	v_rcp_f32_e32 v33, v14
	v_rcp_f32_e32 v35, v27
	v_rcp_f32_e32 v37, v28
	v_rcp_f32_e32 v39, v29
	v_pk_mul_f32 v[18:19], v[32:33], v[18:19]
	v_pk_mul_f32 v[10:11], v[34:35], v[10:11]
	v_pk_mul_f32 v[20:21], v[36:37], v[20:21]
	v_pk_mul_f32 v[22:23], v[38:39], v[22:23]
	v_mov_b32_e32 v28, v15
	s_waitcnt vmcnt(39)
	v_mul_f32_e32 v4, v142, v18
	v_mul_f32_e32 v5, v143, v10
	v_mul_f32_e32 v6, v144, v20
	v_mul_f32_e32 v7, v145, v22
	v_mul_f32_e32 v4, v4, v19
	v_mul_f32_e32 v5, v5, v11
	v_mul_f32_e32 v6, v6, v21
	v_mul_f32_e32 v7, v7, v23
	v_cvt_pk_bf16_f32 v4, v4, v5
	v_cvt_pk_bf16_f32 v5, v6, v7
	global_store_dwordx2 v[8:9], v[4:5], off
	ds_read2_b64 v[4:7], v26 offset0:56 offset1:60
	v_lshl_add_u64 v[18:19], v[12:13], 0, v[24:25]
	v_lshlrev_b32_e32 v23, 16, v139
	v_lshlrev_b32_e32 v21, 16, v138
	v_and_b32_e32 v25, 0xffff0000, v139
	s_waitcnt lgkmcnt(0)
	v_lshlrev_b32_e32 v22, 16, v5
	v_and_b32_e32 v24, 0xffff0000, v5
	v_and_b32_e32 v5, 0xffff0000, v138
	v_mul_f32_e32 v27, 0xbfb8aa3b, v5
	v_mul_f32_e32 v29, 0xbfb8aa3b, v23
	v_mul_f32_e32 v14, 0xbfb8aa3b, v21
	v_mul_f32_e32 v30, 0xbfb8aa3b, v25
	v_exp_f32_e32 v27, v27
	v_exp_f32_e32 v29, v29
	v_exp_f32_e32 v14, v14
	v_exp_f32_e32 v30, v30
	v_add_f32_e32 v31, 1.0, v27
	v_add_f32_e32 v33, 1.0, v29
	v_add_f32_e32 v14, 1.0, v14
	v_add_f32_e32 v30, 1.0, v30
	v_rcp_f32_e32 v29, v31
	v_rcp_f32_e32 v33, v33
	v_rcp_f32_e32 v27, v14
	v_rcp_f32_e32 v35, v30
	v_lshlrev_b32_e32 v20, 16, v4
	v_and_b32_e32 v4, 0xffff0000, v4
	v_mov_b32_e32 v26, v15
	v_pk_mul_f32 v[4:5], v[28:29], v[4:5]
	v_pk_mul_f32 v[22:23], v[32:33], v[22:23]
	v_pk_mul_f32 v[20:21], v[26:27], v[20:21]
	v_pk_mul_f32 v[24:25], v[34:35], v[24:25]
	v_lshlrev_b32_e32 v14, 16, v7
	s_waitcnt vmcnt(39)
	v_mul_f32_e32 v4, v147, v4
	v_mul_f32_e32 v9, v148, v22
	v_mul_f32_e32 v8, v146, v20
	v_mul_f32_e32 v10, v149, v24
	v_mul_f32_e32 v4, v4, v5
	v_mul_f32_e32 v5, v9, v23
	v_mul_f32_e32 v8, v8, v21
	v_mul_f32_e32 v9, v10, v25
	v_cvt_pk_bf16_f32 v4, v8, v4
	v_cvt_pk_bf16_f32 v5, v5, v9
	global_store_dwordx2 v[18:19], v[4:5], off
	v_lshl_add_u64 v[4:5], v[12:13], 0, v[2:3]
	v_and_b32_e32 v18, 0xffff0000, v7
	v_mov_b32_e32 v20, v15
	v_mov_b32_e32 v22, v15
	v_mov_b32_e32 v24, v15
	v_lshlrev_b32_e32 v13, 16, v140
	v_and_b32_e32 v7, 0xffff0000, v140
	v_lshlrev_b32_e32 v15, 16, v141
	v_and_b32_e32 v19, 0xffff0000, v141
	v_mul_f32_e32 v2, 0xbfb8aa3b, v13
	v_mul_f32_e32 v16, 0xbfb8aa3b, v7
	v_mul_f32_e32 v17, 0xbfb8aa3b, v15
	v_mul_f32_e32 v21, 0xbfb8aa3b, v19
	v_exp_f32_e32 v2, v2
	v_exp_f32_e32 v16, v16
	v_exp_f32_e32 v17, v17
	v_exp_f32_e32 v21, v21
	v_add_f32_e32 v2, 1.0, v2
	v_add_f32_e32 v16, 1.0, v16
	v_add_f32_e32 v17, 1.0, v17
	v_add_f32_e32 v27, 1.0, v21
	v_rcp_f32_e32 v21, v2
	v_rcp_f32_e32 v23, v16
	v_rcp_f32_e32 v25, v17
	v_rcp_f32_e32 v27, v27
	v_lshlrev_b32_e32 v12, 16, v6
	v_and_b32_e32 v6, 0xffff0000, v6
	v_pk_mul_f32 v[12:13], v[20:21], v[12:13]
	v_pk_mul_f32 v[6:7], v[22:23], v[6:7]
	v_pk_mul_f32 v[14:15], v[24:25], v[14:15]
	v_pk_mul_f32 v[16:17], v[26:27], v[18:19]
	v_readlane_b32 s4, v244, 32
	v_readlane_b32 s14, v244, 42
	v_readlane_b32 s15, v244, 43
	v_readlane_b32 s16, v244, 44
	v_readlane_b32 s17, v244, 45
	v_readlane_b32 s6, v244, 34
	s_mov_b32 s6, 0xbfb8aa3b
	s_mov_b32 s4, 0x3f2aaaab
	v_readlane_b32 s5, v244, 33
	s_mov_b32 s5, 0x3f317218
	v_readlane_b32 s7, v244, 35
	v_readlane_b32 s8, v244, 36
	v_readlane_b32 s9, v244, 37
	v_readlane_b32 s10, v244, 38
	v_readlane_b32 s11, v244, 39
	v_readlane_b32 s12, v244, 40
	v_readlane_b32 s13, v244, 41
	v_readlane_b32 s18, v244, 46
	v_readlane_b32 s19, v244, 47
	s_waitcnt vmcnt(39)
	v_mul_f32_e32 v2, v150, v12
	v_mul_f32_e32 v6, v151, v6
	v_mul_f32_e32 v8, v152, v14
	v_mul_f32_e32 v9, v153, v16
	v_mul_f32_e32 v6, v6, v7
	v_mul_f32_e32 v7, v8, v15
	v_mul_f32_e32 v2, v2, v13
	v_mul_f32_e32 v8, v9, v17
	v_cvt_pk_bf16_f32 v6, v2, v6
	v_cvt_pk_bf16_f32 v7, v7, v8
	global_store_dwordx2 v[4:5], v[6:7], off
	s_barrier
	s_waitcnt vmcnt(32)
	s_nop 0
	v_ashrrev_i32_e32 v43, 31, v42
	v_lshlrev_b64 v[4:5], 2, v[42:43]
	v_lshl_add_u64 v[6:7], s[42:43], 0, v[4:5]
	v_mov_b32_e32 v2, v154
	v_lshl_add_u64 v[8:9], s[14:15], 0, v[4:5]
	v_add_co_u32_e32 v6, vcc, s0, v8
	v_bfe_u32 v43, v42, 4, 2
	s_nop 0
	v_addc_co_u32_e32 v7, vcc, 0, v9, vcc
	v_mov_b32_e32 v14, v155
	v_mov_b32_e32 v15, v168
	v_mov_b32_e32 v16, v169
	v_mov_b32_e32 v17, v171
	v_and_b32_e32 v18, 0xffffffc0, v42
	v_lshl_or_b32 v104, v43, 3, v18
	v_lshl_add_u64 v[18:19], s[16:17], 0, v[4:5]
	v_lshl_add_u64 v[20:21], s[36:37], 0, v[4:5]
	v_lshl_add_u64 v[4:5], s[40:41], 0, v[4:5]
	v_mov_b32_e32 v18, v240
	s_nop 0
	v_mov_b32_e32 v19, v241
	s_nop 0
	v_mov_b32_e32 v20, v242
	v_lshrrev_b32_e32 v30, 1, v42
	v_and_b32_e32 v31, 1, v42
	v_lshlrev_b32_e32 v30, 6, v30
	v_lshl_or_b32 v30, v31, 2, v30
	v_and_b32_e32 v195, 15, v42
	v_cmp_lt_u32_e32 vcc, 2, v195
	s_or_b64 s[0:1], s[22:23], vcc
	v_mov_b32_e32 v8, v3
	v_mov_b32_e32 v9, v3
	v_mov_b32_e32 v6, v3
	v_mov_b32_e32 v7, v3
	v_mov_b64_e32 v[12:13], v[8:9]
	v_mov_b64_e32 v[10:11], v[6:7]
	v_ashrrev_i32_e32 v105, 31, v104
	v_mul_f32_e64 v4, |v2|, s6
	v_exp_f32_e32 v21, v4
	v_max_f32_e64 v2, -v2, -v2
	v_max_f32_e32 v2, 0, v2
	ds_write2_b32 v30, v14, v15 offset1:2
	ds_write2_b32 v30, v16, v17 offset0:4 offset1:6
	v_add_f32_e32 v14, 1.0, v21
	v_add_f32_e32 v15, -1.0, v14
	v_frexp_mant_f32_e32 v16, v14
	v_cvt_f64_f32_e32 v[4:5], v14
	v_sub_f32_e32 v17, v15, v14
	v_frexp_exp_i32_f64_e32 v4, v[4:5]
	v_cmp_gt_f32_e32 vcc, s4, v16
	v_sub_f32_e32 v15, v21, v15
	v_add_f32_e32 v5, 1.0, v17
	v_subbrev_co_u32_e32 v4, vcc, 0, v4, vcc
	v_add_f32_e32 v5, v15, v5
	v_sub_u32_e32 v15, 0, v4
	v_ldexp_f32 v14, v14, v15
	v_add_f32_e32 v16, -1.0, v14
	v_add_f32_e32 v17, 1.0, v14
	v_ldexp_f32 v5, v5, v15
	v_add_f32_e32 v15, 1.0, v16
	v_add_f32_e32 v22, -1.0, v17
	v_sub_f32_e32 v15, v14, v15
	v_sub_f32_e32 v14, v14, v22
	v_add_f32_e32 v22, v5, v15
	v_add_f32_e32 v5, v5, v14
	v_add_f32_e32 v24, v17, v5
	v_rcp_f32_e32 v25, v24
	v_add_f32_e32 v15, v16, v22
	v_sub_f32_e32 v16, v15, v16
	v_sub_f32_e32 v14, v24, v17
	v_mul_f32_e32 v27, v15, v25
	v_sub_f32_e32 v26, v22, v16
	v_mul_f32_e32 v16, v24, v27
	v_sub_f32_e32 v5, v5, v14
	v_fma_f32 v22, v27, v24, -v16
	v_fmac_f32_e32 v22, v27, v5
	v_add_f32_e32 v14, v16, v22
	v_sub_f32_e32 v17, v15, v14
	v_mov_b32_e32 v23, v14
	v_pk_add_f32 v[14:15], v[14:15], v[16:17] neg_lo:[0,1] neg_hi:[0,1]
	v_cvt_f32_i32_e32 v4, v4
	v_pk_add_f32 v[14:15], v[14:15], v[22:23] neg_lo:[0,1] neg_hi:[0,1]
	v_cmp_neq_f32_e32 vcc, s3, v21
	v_add_f32_e32 v15, v26, v15
	v_add_f32_e32 v14, v14, v15
	v_add_f32_e32 v15, v17, v14
	v_mul_f32_e32 v23, v25, v15
	v_mul_f32_e32 v16, v24, v23
	v_sub_f32_e32 v17, v17, v15
	v_add_f32_e32 v28, v27, v23
	v_fma_f32 v22, v23, v24, -v16
	v_add_f32_e32 v26, v14, v17
	v_sub_f32_e32 v14, v28, v27
	v_fmac_f32_e32 v22, v23, v5
	v_sub_f32_e32 v5, v23, v14
	v_add_f32_e32 v14, v16, v22
	v_sub_f32_e32 v17, v15, v14
	v_mov_b32_e32 v23, v14
	v_pk_add_f32 v[14:15], v[14:15], v[16:17] neg_lo:[0,1] neg_hi:[0,1]
	s_nop 0
	v_pk_add_f32 v[14:15], v[14:15], v[22:23] neg_lo:[0,1] neg_hi:[0,1]
	s_nop 0
	v_add_f32_e32 v15, v26, v15
	v_add_f32_e32 v14, v14, v15
	v_add_f32_e32 v14, v17, v14
	v_mul_f32_e32 v14, v25, v14
	v_add_f32_e32 v5, v5, v14
	v_add_f32_e32 v14, v28, v5
	v_mul_f32_e32 v16, v14, v14
	v_sub_f32_e32 v17, v14, v28
	v_fmamk_f32 v22, v16, 0x3e9b6dac, v181
	v_sub_f32_e32 v17, v5, v17
	v_mul_f32_e32 v5, v14, v16
	v_fmaak_f32 v113, v16, v22, 0x3f2aaada
	v_ldexp_f32 v23, v17, 1
	v_pk_mul_f32 v[16:17], v[4:5], v[112:113]
	v_ldexp_f32 v15, v14, 1
	v_fma_f32 v14, v4, s5, -v16
	v_fmac_f32_e32 v14, 0xb102e308, v4
	v_pk_add_f32 v[4:5], v[16:17], v[14:15]
	v_mov_b32_e32 v22, v16
	v_sub_f32_e32 v26, v5, v15
	v_pk_add_f32 v[24:25], v[4:5], v[16:17] neg_lo:[0,1] neg_hi:[0,1]
	v_sub_f32_e32 v16, v17, v26
	v_add_f32_e32 v23, v23, v16
	v_pk_add_f32 v[16:17], v[4:5], v[22:23]
	v_mov_b32_e32 v15, v4
	v_mov_b32_e32 v25, v17
	v_pk_add_f32 v[28:29], v[14:15], v[24:25] neg_lo:[0,1] neg_hi:[0,1]
	v_pk_add_f32 v[14:15], v[14:15], v[24:25]
	v_mov_b32_e32 v27, v4
	v_pk_add_f32 v[24:25], v[14:15], v[4:5] op_sel:[1,0] op_sel_hi:[0,1] neg_lo:[0,1] neg_hi:[0,1]
	v_mov_b32_e32 v26, v23
	v_mov_b32_e32 v22, v17
	v_mov_b32_e32 v23, v15
	v_pk_mov_b32 v[4:5], v[4:5], v[24:25] op_sel:[1,0]
	v_pk_add_f32 v[16:17], v[16:17], v[24:25] op_sel_hi:[1,0] neg_lo:[0,1] neg_hi:[0,1]
	v_pk_add_f32 v[4:5], v[22:23], v[4:5] neg_lo:[0,1] neg_hi:[0,1]
	v_mov_b32_e32 v16, v28
	v_pk_add_f32 v[4:5], v[26:27], v[4:5] neg_lo:[0,1] neg_hi:[0,1]
	v_mov_b32_e32 v29, v15
	v_pk_add_f32 v[16:17], v[16:17], v[4:5]
	s_nop 0
	v_pk_add_f32 v[22:23], v[16:17], v[16:17] op_sel:[0,1] op_sel_hi:[1,0]
	s_nop 0
	v_pk_add_f32 v[14:15], v[14:15], v[22:23] op_sel:[1,0] op_sel_hi:[0,1]
	v_mov_b32_e32 v17, v14
	v_mov_b32_e32 v5, v22
	v_pk_add_f32 v[22:23], v[16:17], v[28:29] neg_lo:[0,1] neg_hi:[0,1]
	s_nop 0
	v_sub_f32_e32 v15, v16, v22
	v_pk_add_f32 v[4:5], v[4:5], v[22:23] neg_lo:[0,1] neg_hi:[0,1]
	v_sub_f32_e32 v15, v28, v15
	v_add_f32_e32 v4, v4, v15
	v_add_f32_e32 v4, v4, v5
	v_add_f32_e32 v4, v14, v4
	v_cndmask_b32_e32 v4, v185, v4, vcc
	v_cmp_ngt_f32_e32 vcc, -1.0, v21
	v_mov_b64_e32 v[16:17], v[8:9]
	v_mov_b64_e32 v[14:15], v[6:7]
	v_cndmask_b32_e32 v4, v186, v4, vcc
	v_cmp_neq_f32_e32 vcc, -1.0, v21
	s_nop 1
	v_cndmask_b32_e32 v4, v187, v4, vcc
	v_cmp_lt_f32_e64 vcc, |v21|, s2
	s_nop 1
	v_cndmask_b32_e32 v4, v4, v21, vcc
	v_add_f32_e32 v2, v2, v4
	v_mul_f32_e32 v21, 0xc1000000, v2
	ds_write2_b32 v30, v18, v19 offset0:8 offset1:10
	ds_write2_b32 v30, v20, v21 offset0:12 offset1:14
	s_and_saveexec_b64 s[2:3], s[0:1]
	s_cbranch_execz .LBB0_217
	v_add3_u32 v2, s20, -3, v195
	v_mov_b64_e32 v[4:5], s[88:89]
	v_mad_i64_i32 v[4:5], s[0:1], v2, s92, v[4:5]
	v_lshl_add_u64 v[4:5], v[104:105], 1, v[4:5]
	global_load_dwordx4 v[14:17], v[4:5], off
	global_load_dwordx4 v[10:13], v[4:5], off offset:64

.LBB0_221:
	s_or_b64 exec, exec, s[0:1]
	v_ashrrev_i32_e32 v4, 6, v42
	v_ashrrev_i32_e32 v5, 31, v4
	v_readlane_b32 s0, v244, 48
	v_and_b32_e32 v2, 63, v42
	v_lshlrev_b64 v[30:31], 13, v[4:5]
	v_readlane_b32 s1, v244, 49
	v_lshlrev_b32_e32 v2, 4, v2
	v_and_b32_e32 v5, 7, v42
	v_lshl_add_u64 v[30:31], s[0:1], 0, v[30:31]
	s_mov_b64 s[0:1], 0x10000
	v_lshl_add_u64 v[32:33], v[30:31], 0, s[0:1]
	v_lshl_add_u64 v[34:35], v[30:31], 0, v[2:3]
	v_lshl_add_u64 v[36:37], v[32:33], 0, v[2:3]
	v_or_b32_e32 v34, 0x1000, v2
	v_mov_b32_e32 v35, v3
	v_lshl_add_u64 v[36:37], v[30:31], 0, v[34:35]
	v_lshl_add_u64 v[34:35], v[32:33], 0, v[34:35]
	v_or_b32_e32 v34, 0x1400, v2
	v_mov_b32_e32 v35, v3
	v_lshl_add_u64 v[36:37], v[30:31], 0, v[34:35]
	v_lshl_add_u64 v[34:35], v[32:33], 0, v[34:35]
	v_or_b32_e32 v34, 0x1800, v2
	v_mov_b32_e32 v35, v3
	v_lshl_add_u64 v[36:37], v[30:31], 0, v[34:35]
	v_lshl_add_u64 v[34:35], v[32:33], 0, v[34:35]
	v_or_b32_e32 v34, 0x1c00, v2
	v_mov_b32_e32 v35, v3
	v_lshl_add_u64 v[30:31], v[30:31], 0, v[34:35]
	v_lshl_add_u64 v[32:33], v[32:33], 0, v[34:35]
	v_mov_b64_e32 v[30:31], s[88:89]
	v_lshrrev_b32_e32 v32, 4, v42
	v_bfe_u32 v33, v42, 4, 1
	v_mad_i64_i32 v[30:31], s[0:1], v113, s92, v[30:31]
	v_bitop3_b32 v34, v32, v5, 1 bitop3:0x6c
	v_bitop3_b32 v35, v33, v5, 2 bitop3:0x36
	v_bitop3_b32 v36, v33, v5, 4 bitop3:0x36
	v_bitop3_b32 v5, v33, v5, 6 bitop3:0x36
	v_lshl_add_u64 v[32:33], v[104:105], 1, v[30:31]
	v_lshl_add_u64 v[30:31], v[106:107], 1, v[30:31]
	v_lshlrev_b32_e32 v109, 4, v34
	v_lshlrev_b32_e32 v111, 4, v35
	v_lshlrev_b32_e32 v115, 4, v36
	global_load_dwordx4 v[34:37], v[32:33], off
	s_nop 0
	global_load_dwordx4 v[30:33], v[30:31], off
	s_movk_i32 s2, 0x780
	s_movk_i32 s3, 0xb80
	s_movk_i32 s4, 0xf80
	s_movk_i32 s5, 0x1380
	v_lshl_add_u32 v4, v4, 14, 0
	v_and_b32_e32 v108, 0x380, v2
	s_movk_i32 s6, 0x1780
	v_bitop3_b32 v110, v2, s2, v188 bitop3:0xc8
	v_bitop3_b32 v114, v2, s3, v189 bitop3:0xc8
	v_bitop3_b32 v116, v2, s4, v190 bitop3:0xc8
	v_lshlrev_b32_e32 v5, 4, v5
	v_bitop3_b32 v117, v2, s5, v191 bitop3:0xc8
	v_add3_u32 v108, v4, v108, v109
	v_add3_u32 v110, v4, v110, v111
	v_add3_u32 v114, v4, v114, v115
	v_add3_u32 v116, v4, v116, v5
	v_add3_u32 v109, v4, v117, v109
	s_movk_i32 s0, 0x1b80
	s_mov_b32 s2, 0xbfb8aa3b
	s_waitcnt vmcnt(18)
	ds_write_b128 v108, v[156:159] offset:16384
	ds_write_b128 v110, v[160:163] offset:16384
	ds_write_b128 v114, v[164:167] offset:16384
	ds_write_b128 v116, v[172:175] offset:16384
	ds_write_b128 v109, v[212:215] offset:16384
	ds_write_b128 v108, v[196:199] offset:24576
	ds_write_b128 v110, v[200:203] offset:24576
	ds_write_b128 v114, v[204:207] offset:24576
	ds_write_b128 v116, v[208:211] offset:24576
	ds_write_b128 v109, v[216:219] offset:24576
	v_bitop3_b32 v38, v2, s6, v192 bitop3:0xc8
	v_add3_u32 v38, v4, v38, v111
	ds_write_b128 v38, v[220:223] offset:16384
	ds_write_b128 v38, v[224:227] offset:24576
	v_bitop3_b32 v38, v2, s0, v193 bitop3:0xc8
	s_movk_i32 s0, 0x1f80
	v_bitop3_b32 v2, v2, s0, v194 bitop3:0xc8
	v_add3_u32 v38, v4, v38, v115
	v_add3_u32 v2, v4, v2, v5
	v_lshlrev_b32_e32 v5, 5, v104
	ds_write_b128 v38, v[228:231] offset:16384
	ds_write_b128 v38, v[232:235] offset:24576
	ds_write_b128 v2, v[236:239] offset:16384
	ds_write_b128 v2, v[248:251] offset:24576
	v_add_u32_e32 v2, 0, v5
	v_or_b32_e32 v38, 4, v5
	v_mov_b32_e32 v239, 0
	v_mov_b32_e32 v179, 1.0
	v_mov_b32_e32 v236, 1.0
	v_mov_b32_e32 v237, 1.0
	v_mov_b32_e32 v238, 1.0
	v_mov_b32_e32 v228, 1.0
	v_mov_b32_e32 v229, 1.0
	v_mov_b32_e32 v230, 1.0
	v_mov_b32_e32 v231, 1.0
	v_mov_b32_e32 v220, 1.0
	v_mov_b32_e32 v221, 1.0
	v_mov_b32_e32 v222, 1.0
	v_mov_b32_e32 v223, 1.0
	v_mov_b32_e32 v171, 1.0
	v_mov_b32_e32 v213, 1.0
	v_mov_b32_e32 v214, 1.0
	v_mov_b32_e32 v215, 1.0
	v_mov_b32_e32 v240, 0
	v_mov_b32_e32 v241, 0
	s_waitcnt lgkmcnt(0)
	s_barrier
	v_add_u32_e32 v196, 0, v38
	ds_read2_b32 v[38:39], v2 offset0:10 offset1:12
	ds_read2_b32 v[40:41], v196 offset0:10 offset1:12
	ds_read_b32 v44, v2 offset:56
	ds_read_b32 v45, v196 offset:56
	s_mov_b32 s0, 0x3fb8aa3b
	s_waitcnt lgkmcnt(3)
	v_mov_b32_e32 v46, v38
	v_or_b32_e32 v38, 64, v5
	s_waitcnt lgkmcnt(2)
	v_mov_b32_e32 v47, v40
	v_mov_b32_e32 v40, v39
	v_add_u32_e32 v197, 0, v38
	v_or_b32_e32 v38, 0x44, v5
	v_pk_mul_f32 v[110:111], v[40:41], s[2:3] op_sel_hi:[1,0]
	v_add_u32_e32 v198, 0, v38
	ds_read2_b32 v[38:39], v197 offset0:10 offset1:12
	ds_read2_b32 v[40:41], v198 offset0:10 offset1:12
	v_pk_mul_f32 v[108:109], v[46:47], s[2:3] op_sel_hi:[1,0]
	s_waitcnt lgkmcnt(2)
	v_pk_mul_f32 v[114:115], v[44:45], s[0:1] op_sel_hi:[1,0]
	ds_read_b32 v44, v197 offset:56
	ds_read_b32 v45, v198 offset:56
	s_waitcnt lgkmcnt(3)
	v_mov_b32_e32 v46, v38
	v_or_b32_e32 v38, 0x80, v5
	s_waitcnt lgkmcnt(2)
	v_mov_b32_e32 v47, v40
	v_mov_b32_e32 v40, v39
	v_add_u32_e32 v199, 0, v38
	v_or_b32_e32 v38, 0x84, v5
	v_pk_mul_f32 v[118:119], v[40:41], s[2:3] op_sel_hi:[1,0]
	v_add_u32_e32 v200, 0, v38
	ds_read2_b32 v[38:39], v199 offset0:10 offset1:12
	ds_read2_b32 v[40:41], v200 offset0:10 offset1:12
	v_pk_mul_f32 v[116:117], v[46:47], s[2:3] op_sel_hi:[1,0]
	s_waitcnt lgkmcnt(2)
	v_pk_mul_f32 v[120:121], v[44:45], s[0:1] op_sel_hi:[1,0]
	ds_read_b32 v44, v199 offset:56
	ds_read_b32 v45, v200 offset:56
	s_waitcnt lgkmcnt(3)
	v_mov_b32_e32 v46, v38
	v_or_b32_e32 v38, 0xc0, v5
	s_waitcnt lgkmcnt(2)
	v_mov_b32_e32 v47, v40
	v_mov_b32_e32 v40, v39
	v_add_u32_e32 v201, 0, v38
	v_or_b32_e32 v38, 0xc4, v5
	v_pk_mul_f32 v[124:125], v[40:41], s[2:3] op_sel_hi:[1,0]
	v_add_u32_e32 v202, 0, v38
	ds_read2_b32 v[38:39], v201 offset0:10 offset1:12
	ds_read2_b32 v[40:41], v202 offset0:10 offset1:12
	v_pk_mul_f32 v[122:123], v[46:47], s[2:3] op_sel_hi:[1,0]
	s_waitcnt lgkmcnt(2)
	v_pk_mul_f32 v[126:127], v[44:45], s[0:1] op_sel_hi:[1,0]
	ds_read_b32 v44, v201 offset:56
	ds_read_b32 v45, v202 offset:56
	s_waitcnt lgkmcnt(3)
	v_mov_b32_e32 v46, v38
	v_lshlrev_b32_e32 v38, 5, v106
	s_waitcnt lgkmcnt(2)
	v_mov_b32_e32 v47, v40
	v_mov_b32_e32 v40, v39
	v_add_u32_e32 v203, 0, v38
	v_or_b32_e32 v38, 0x404, v5
	v_pk_mul_f32 v[130:131], v[40:41], s[2:3] op_sel_hi:[1,0]
	v_add_u32_e32 v204, 0, v38
	ds_read2_b32 v[38:39], v203 offset0:10 offset1:12
	ds_read2_b32 v[40:41], v204 offset0:10 offset1:12
	v_pk_mul_f32 v[128:129], v[46:47], s[2:3] op_sel_hi:[1,0]
	s_waitcnt lgkmcnt(2)
	v_pk_mul_f32 v[132:133], v[44:45], s[0:1] op_sel_hi:[1,0]
	ds_read_b32 v44, v203 offset:56
	ds_read_b32 v45, v204 offset:56
	s_waitcnt lgkmcnt(3)
	v_mov_b32_e32 v46, v38
	v_or_b32_e32 v38, 0x440, v5
	s_waitcnt lgkmcnt(2)
	v_mov_b32_e32 v47, v40
	v_mov_b32_e32 v40, v39
	v_add_u32_e32 v205, 0, v38
	v_or_b32_e32 v38, 0x444, v5
	v_pk_mul_f32 v[136:137], v[40:41], s[2:3] op_sel_hi:[1,0]
	v_add_u32_e32 v206, 0, v38
	ds_read2_b32 v[38:39], v205 offset0:10 offset1:12
	ds_read2_b32 v[40:41], v206 offset0:10 offset1:12
	v_pk_mul_f32 v[134:135], v[46:47], s[2:3] op_sel_hi:[1,0]
	s_waitcnt lgkmcnt(2)
	v_pk_mul_f32 v[138:139], v[44:45], s[0:1] op_sel_hi:[1,0]
	ds_read_b32 v44, v205 offset:56
	ds_read_b32 v45, v206 offset:56
	s_waitcnt lgkmcnt(3)
	v_mov_b32_e32 v46, v38
	v_or_b32_e32 v38, 0x480, v5
	s_waitcnt lgkmcnt(2)
	v_mov_b32_e32 v47, v40
	v_mov_b32_e32 v40, v39
	v_add_u32_e32 v207, 0, v38
	v_or_b32_e32 v38, 0x484, v5
	v_pk_mul_f32 v[142:143], v[40:41], s[2:3] op_sel_hi:[1,0]
	v_add_u32_e32 v208, 0, v38
	ds_read2_b32 v[38:39], v207 offset0:10 offset1:12
	ds_read2_b32 v[40:41], v208 offset0:10 offset1:12
	v_pk_mul_f32 v[140:141], v[46:47], s[2:3] op_sel_hi:[1,0]
	s_waitcnt lgkmcnt(2)
	v_pk_mul_f32 v[144:145], v[44:45], s[0:1] op_sel_hi:[1,0]
	ds_read_b32 v44, v207 offset:56
	ds_read_b32 v45, v208 offset:56
	s_waitcnt lgkmcnt(3)
	v_mov_b32_e32 v46, v38
	v_or_b32_e32 v38, 0x4c0, v5
	s_waitcnt lgkmcnt(2)
	v_mov_b32_e32 v47, v40
	v_mov_b32_e32 v40, v39
	v_add_u32_e32 v209, 0, v38
	v_or_b32_e32 v5, 0x4c4, v5
	v_pk_mul_f32 v[148:149], v[40:41], s[2:3] op_sel_hi:[1,0]
	v_add_u32_e32 v210, 0, v5
	ds_read2_b32 v[38:39], v209 offset0:10 offset1:12
	ds_read2_b32 v[40:41], v210 offset0:10 offset1:12
	s_waitcnt lgkmcnt(2)
	v_pk_mul_f32 v[150:151], v[44:45], s[0:1] op_sel_hi:[1,0]
	ds_read_b32 v44, v209 offset:56
	ds_read_b32 v45, v210 offset:56
	v_pk_mul_f32 v[146:147], v[46:47], s[2:3] op_sel_hi:[1,0]
	s_waitcnt lgkmcnt(3)
	v_mov_b32_e32 v46, v38
	v_lshlrev_b32_e32 v5, 1, v195
	v_and_b32_e32 v38, 3, v42
	s_waitcnt lgkmcnt(2)
	v_mov_b32_e32 v47, v40
	v_mov_b32_e32 v40, v39
	v_and_or_b32 v5, v5, 24, v38
	v_lshrrev_b32_e32 v38, 1, v42
	v_bfe_u32 v39, v42, 1, 3
	v_bitop3_b32 v38, v43, v38, 7 bitop3:0x78
	v_lshl_add_u32 v4, v5, 7, v4
	v_bitop3_b32 v5, v43, v39, 4 bitop3:0x36
	v_lshlrev_b32_e32 v38, 4, v38
	v_lshlrev_b32_e32 v5, 4, v5
	v_pk_mul_f32 v[152:153], v[46:47], s[2:3] op_sel_hi:[1,0]
	v_pk_mul_f32 v[154:155], v[40:41], s[2:3] op_sel_hi:[1,0]
	s_waitcnt lgkmcnt(0)
	v_pk_mul_f32 v[156:157], v[44:45], s[0:1] op_sel_hi:[1,0]
	s_mov_b32 s2, 0
	v_add_u32_e32 v211, v4, v38
	v_add_u32_e32 v212, v4, v5
	v_mov_b32_e32 v242, 0
	v_mov_b32_e32 v232, 0
	v_mov_b32_e32 v233, 0
	v_mov_b32_e32 v234, 0
	v_mov_b32_e32 v235, 0
	v_mov_b32_e32 v224, 0
	v_mov_b32_e32 v225, 0
	v_mov_b32_e32 v226, 0
	v_mov_b32_e32 v227, 0
	v_mov_b32_e32 v216, 0
	v_mov_b32_e32 v217, 0
	v_mov_b32_e32 v218, 0
	v_mov_b32_e32 v219, 0
	s_waitcnt vmcnt(0)
	s_branch .LBB0_223

.LBB0_223:
	ds_read_b128 v[38:41], v2
	ds_read_b128 v[42:45], v2 offset:16
	ds_read_b64 v[4:5], v2 offset:32
	ds_read_b128 v[46:49], v2 offset:64
	ds_read_b128 v[50:53], v2 offset:80
	ds_read_b64 v[78:79], v2 offset:96
	ds_read_b128 v[54:57], v2 offset:128
	ds_read_b128 v[58:61], v2 offset:144
	ds_read_b64 v[174:175], v2 offset:160
	ds_read_b128 v[62:65], v2 offset:192
	ds_read_b128 v[66:69], v2 offset:208
	ds_read_b64 v[176:177], v2 offset:224
	ds_read_b128 v[70:73], v203
	ds_read_b128 v[74:77], v203 offset:16
	ds_read_b64 v[162:163], v203 offset:32
	ds_read_b128 v[80:83], v203 offset:64
	ds_read_b128 v[84:87], v203 offset:80
	ds_read_b64 v[168:169], v203 offset:96
	ds_read_b128 v[88:91], v203 offset:128
	ds_read_b128 v[92:95], v203 offset:144
	ds_read_b64 v[158:159], v203 offset:160
	ds_read_b128 v[96:99], v203 offset:192
	ds_read_b128 v[100:103], v203 offset:208
	ds_read_b64 v[160:161], v203 offset:224
	s_waitcnt vmcnt(4)
	s_waitcnt lgkmcnt(15)
	v_lshlrev_b32_e32 v252, 16, v14
	v_and_b32_e32 v253, 0xffff0000, v14
	v_pk_fma_f32 v[4:5], v[38:39], v[252:253], v[4:5]
	v_lshlrev_b32_e32 v254, 16, v18
	v_and_b32_e32 v255, 0xffff0000, v18
	v_pk_fma_f32 v[4:5], v[40:41], v[254:255], v[4:5]
	v_lshlrev_b32_e32 v252, 16, v22
	v_and_b32_e32 v253, 0xffff0000, v22
	v_pk_fma_f32 v[4:5], v[42:43], v[252:253], v[4:5]
	v_lshlrev_b32_e32 v254, 16, v34
	v_and_b32_e32 v255, 0xffff0000, v34
	v_pk_fma_f32 v[4:5], v[44:45], v[254:255], v[4:5]
	s_waitcnt lgkmcnt(15)
	v_lshlrev_b32_e32 v252, 16, v15
	v_and_b32_e32 v253, 0xffff0000, v15
	v_pk_fma_f32 v[78:79], v[46:47], v[252:253], v[78:79]
	v_lshlrev_b32_e32 v254, 16, v19
	v_and_b32_e32 v255, 0xffff0000, v19
	v_pk_fma_f32 v[78:79], v[48:49], v[254:255], v[78:79]
	v_lshlrev_b32_e32 v252, 16, v23
	v_and_b32_e32 v253, 0xffff0000, v23
	v_pk_fma_f32 v[78:79], v[50:51], v[252:253], v[78:79]
	v_lshlrev_b32_e32 v254, 16, v35
	v_and_b32_e32 v255, 0xffff0000, v35
	v_pk_fma_f32 v[78:79], v[52:53], v[254:255], v[78:79]
	s_waitcnt lgkmcnt(15)
	v_lshlrev_b32_e32 v252, 16, v16
	v_and_b32_e32 v253, 0xffff0000, v16
	v_pk_fma_f32 v[174:175], v[54:55], v[252:253], v[174:175]
	v_lshlrev_b32_e32 v254, 16, v20
	v_and_b32_e32 v255, 0xffff0000, v20
	v_pk_fma_f32 v[174:175], v[56:57], v[254:255], v[174:175]
	v_lshlrev_b32_e32 v252, 16, v24
	v_and_b32_e32 v253, 0xffff0000, v24
	v_pk_fma_f32 v[174:175], v[58:59], v[252:253], v[174:175]
	v_lshlrev_b32_e32 v254, 16, v36
	v_and_b32_e32 v255, 0xffff0000, v36
	v_pk_fma_f32 v[174:175], v[60:61], v[254:255], v[174:175]
	s_waitcnt lgkmcnt(12)
	v_lshlrev_b32_e32 v252, 16, v17
	v_and_b32_e32 v253, 0xffff0000, v17
	v_pk_fma_f32 v[176:177], v[62:63], v[252:253], v[176:177]
	v_lshlrev_b32_e32 v254, 16, v21
	v_and_b32_e32 v255, 0xffff0000, v21
	v_pk_fma_f32 v[176:177], v[64:65], v[254:255], v[176:177]
	v_lshlrev_b32_e32 v252, 16, v25
	v_and_b32_e32 v253, 0xffff0000, v25
	v_pk_fma_f32 v[176:177], v[66:67], v[252:253], v[176:177]
	v_lshlrev_b32_e32 v254, 16, v37
	v_and_b32_e32 v255, 0xffff0000, v37
	v_pk_fma_f32 v[176:177], v[68:69], v[254:255], v[176:177]
	ds_read_b128 v[46:49], v211 offset:24576
	ds_read_b128 v[38:41], v211 offset:16384
	ds_read_b128 v[50:53], v212 offset:16384
	ds_read_b128 v[54:57], v211 offset:16896
	ds_read_b128 v[62:65], v211 offset:25088
	ds_read_b128 v[66:69], v212 offset:16896
	s_waitcnt lgkmcnt(15)
	v_lshlrev_b32_e32 v252, 16, v10
	v_and_b32_e32 v253, 0xffff0000, v10
	v_pk_fma_f32 v[162:163], v[70:71], v[252:253], v[162:163]
	v_lshlrev_b32_e32 v254, 16, v6
	v_and_b32_e32 v255, 0xffff0000, v6
	v_pk_fma_f32 v[162:163], v[72:73], v[254:255], v[162:163]
	v_lshlrev_b32_e32 v252, 16, v26
	v_and_b32_e32 v253, 0xffff0000, v26
	v_pk_fma_f32 v[162:163], v[74:75], v[252:253], v[162:163]
	v_lshlrev_b32_e32 v254, 16, v30
	v_and_b32_e32 v255, 0xffff0000, v30
	v_pk_fma_f32 v[162:163], v[76:77], v[254:255], v[162:163]
	s_waitcnt lgkmcnt(12)
	v_lshlrev_b32_e32 v252, 16, v11
	v_and_b32_e32 v253, 0xffff0000, v11
	v_pk_fma_f32 v[168:169], v[80:81], v[252:253], v[168:169]
	v_lshlrev_b32_e32 v254, 16, v7
	v_and_b32_e32 v255, 0xffff0000, v7
	v_pk_fma_f32 v[168:169], v[82:83], v[254:255], v[168:169]
	v_lshlrev_b32_e32 v252, 16, v27
	v_and_b32_e32 v253, 0xffff0000, v27
	v_pk_fma_f32 v[168:169], v[84:85], v[252:253], v[168:169]
	v_lshlrev_b32_e32 v254, 16, v31
	v_and_b32_e32 v255, 0xffff0000, v31
	v_pk_fma_f32 v[168:169], v[86:87], v[254:255], v[168:169]
	s_waitcnt lgkmcnt(9)
	v_lshlrev_b32_e32 v252, 16, v12
	v_and_b32_e32 v253, 0xffff0000, v12
	v_pk_fma_f32 v[158:159], v[88:89], v[252:253], v[158:159]
	v_lshlrev_b32_e32 v254, 16, v8
	v_and_b32_e32 v255, 0xffff0000, v8
	v_pk_fma_f32 v[158:159], v[90:91], v[254:255], v[158:159]
	v_lshlrev_b32_e32 v252, 16, v28
	v_and_b32_e32 v253, 0xffff0000, v28
	v_pk_fma_f32 v[158:159], v[92:93], v[252:253], v[158:159]
	v_lshlrev_b32_e32 v254, 16, v32
	v_and_b32_e32 v255, 0xffff0000, v32
	v_pk_fma_f32 v[158:159], v[94:95], v[254:255], v[158:159]
	s_waitcnt lgkmcnt(6)
	v_lshlrev_b32_e32 v252, 16, v13
	v_and_b32_e32 v253, 0xffff0000, v13
	v_pk_fma_f32 v[160:161], v[96:97], v[252:253], v[160:161]
	v_lshlrev_b32_e32 v254, 16, v9
	v_and_b32_e32 v255, 0xffff0000, v9
	v_pk_fma_f32 v[160:161], v[98:99], v[254:255], v[160:161]
	v_lshlrev_b32_e32 v252, 16, v29
	v_and_b32_e32 v253, 0xffff0000, v29
	v_pk_fma_f32 v[160:161], v[100:101], v[252:253], v[160:161]
	v_lshlrev_b32_e32 v254, 16, v33
	v_and_b32_e32 v255, 0xffff0000, v33
	v_pk_fma_f32 v[160:161], v[102:103], v[254:255], v[160:161]
	s_cmpk_eq_i32 s2, 0x70
	s_cbranch_scc1 .Llru_noload
	v_add3_u32 v248, v113, s2, 13
	v_mul_u32_u24_e32 v248, 0x1200, v248
	v_lshl_add_u32 v248, v104, 1, v248
	v_add_u32_e32 v249, 0x1200, v248
	v_add_u32_e32 v250, 0x2400, v248
	v_add_u32_e32 v251, 0x3600, v248
	global_load_dwordx4 v[14:17], v248, s[88:89]
	global_load_dwordx4 v[10:13], v248, s[88:89] offset:64
	global_load_dwordx4 v[18:21], v249, s[88:89]
	global_load_dwordx4 v[6:9], v249, s[88:89] offset:64
	global_load_dwordx4 v[22:25], v250, s[88:89]
	global_load_dwordx4 v[26:29], v250, s[88:89] offset:64
	global_load_dwordx4 v[34:37], v251, s[88:89]
	global_load_dwordx4 v[30:33], v251, s[88:89] offset:64
